# v16 + w_in_b transposes loop rewritten: loads two tiles ahead (two register sets, unrolled x2)
# baseline (speedup 1.0000x reference)
; #define LAS __attribute__((address_space(3)))
; template <bool REMAP = false>
; __device__ __forceinline__ void transpose_convert(LAS unsigned char* lds, const float* src, bf16_t* dst, int K, int N, int G, int bid) {
;     LAS float* tile = (LAS float*)lds;
;     const int tid = threadIdx.x, ntn = N / 64, ntiles = (K / 128) * ntn;
;     const int r0 = tid >> 4, c4 = tid & 15;
;     f32x4 v[4];
;     if (bid < ntiles) { const int k0 = (bid / ntn) * 128, n0 = (bid % ntn) * 64;
; #pragma unroll
;         for (int i = 0; i < 4; ++i) v[i] = __builtin_nontemporal_load((const f32x4*)(src + (size_t)(k0 + r0 + 32 * i) * N + n0 + c4 * 4)); }
;     for (int t = bid; t < ntiles; t += G) {
;         const int k0 = (t / ntn) * 128, n0 = (t % ntn) * 64;
;         asm volatile("s_waitcnt lgkmcnt(0)" ::: "memory"); __builtin_amdgcn_s_barrier(); asm volatile("" ::: "memory");
; #pragma unroll
;         for (int i = 0; i < 4; ++i) {
; #pragma unroll
;             for (int j = 0; j < 4; ++j) tile[(r0 + 32 * i) * 65 + c4 * 4 + j] = v[i][j]; }
;         asm volatile("s_waitcnt lgkmcnt(0)" ::: "memory"); __builtin_amdgcn_s_barrier(); asm volatile("" ::: "memory");
;         if (t + G < ntiles) { const int k1 = ((t + G) / ntn) * 128, n1 = ((t + G) % ntn) * 64;
; #pragma unroll
;             for (int i = 0; i < 4; ++i) v[i] = __builtin_nontemporal_load((const f32x4*)(src + (size_t)(k1 + r0 + 32 * i) * N + n1 + c4 * 4)); }
.Lrk5_done:
	s_mul_i32 s4, s4, s100
	s_add_i32 s99, s5, s4
	s_add_i32 s100, s99, s100
	v_lshlrev_b32_e32 v18, 4, v20
	v_mov_b32_e32 v19, 0
	s_mov_b32 s3, 0x100000
	s_mov_b32 s16, 0x300000
	v_add_u32_e32 v21, 0x200, v164
	v_add_u32_e32 v22, 0, v18
	v_lshrrev_b32_e32 v21, 4, v21
	v_mul_u32_u24_e32 v23, 0x104, v214
	v_lshl_add_u32 v27, v21, 2, 0
	v_mul_u32_u24_e32 v28, 0x820, v20
	v_lshl_add_u32 v26, v214, 2, 0
	v_add_u32_e32 v22, v22, v23
	v_lshl_add_u64 v[16:17], s[30:31], 0, v[18:19]
	v_lshl_add_u64 v[18:19], s[40:41], 0, v[18:19]
	v_add_u32_e32 v23, 0x2080, v22
	v_add_u32_e32 v24, 0x2088, v22
	v_add_u32_e32 v25, 0x4100, v22
	v_add_u32_e32 v26, v26, v28
	v_add_u32_e32 v27, v27, v28
	v_add_u32_e32 v28, 0x4108, v22
	v_add_u32_e32 v29, 0x6180, v22
	v_add_u32_e32 v47, 0x6188, v22
	s_mov_b32 s19, s99
	s_waitcnt vmcnt(0)
	s_and_b32 s7, s19, 0xffffff80
	s_lshl_b32 s23, s19, 6
	s_and_b32 s6, s23, 0xffffe000
	s_sub_i32 s6, s23, s6
	v_or_b32_e32 v8, s7, v214
	s_ashr_i32 s7, s6, 31
	v_ashrrev_i32_e32 v9, 31, v8
	v_lshl_add_u64 v[10:11], s[6:7], 2, v[16:17]
	v_lshlrev_b64 v[0:1], 15, v[8:9]
	v_lshl_add_u64 v[12:13], v[10:11], 0, v[0:1]
	v_or_b32_e32 v8, 64, v8
	v_add_co_u32_e32 v14, vcc, s3, v12
	v_ashrrev_i32_e32 v9, 31, v8
	s_nop 0
	v_addc_co_u32_e32 v15, vcc, 0, v13, vcc
	v_lshlrev_b64 v[8:9], 15, v[8:9]
	v_lshl_add_u64 v[30:31], v[10:11], 0, v[8:9]
	v_add_co_u32_e32 v32, vcc, s16, v12
	global_load_dwordx4 v[0:3], v[12:13], off nt
	global_load_dwordx4 v[4:7], v[14:15], off nt
	v_addc_co_u32_e32 v33, vcc, 0, v13, vcc
	global_load_dwordx4 v[8:11], v[30:31], off nt
	global_load_dwordx4 v[12:15], v[32:33], off nt
	s_add_i32 s22, s19, 1
	s_cmp_lt_i32 s22, s100
	s_cbranch_scc0 .Lt5_a
	s_and_b32 s7, s22, 0xffffff80
	s_lshl_b32 s23, s22, 6
	s_and_b32 s6, s23, 0xffffe000
	s_sub_i32 s6, s23, s6
	v_or_b32_e32 v74, s7, v214
	s_ashr_i32 s7, s6, 31
	v_ashrrev_i32_e32 v75, 31, v74
	v_lshl_add_u64 v[76:77], s[6:7], 2, v[16:17]
	v_lshlrev_b64 v[66:67], 15, v[74:75]
	v_lshl_add_u64 v[78:79], v[76:77], 0, v[66:67]
	v_or_b32_e32 v74, 64, v74
	v_add_co_u32_e32 v80, vcc, s3, v78
	v_ashrrev_i32_e32 v75, 31, v74
	s_nop 0
	v_addc_co_u32_e32 v81, vcc, 0, v79, vcc
	v_lshlrev_b64 v[74:75], 15, v[74:75]
	v_lshl_add_u64 v[30:31], v[76:77], 0, v[74:75]
	v_add_co_u32_e32 v32, vcc, s16, v78
	global_load_dwordx4 v[66:69], v[78:79], off nt
	global_load_dwordx4 v[70:73], v[80:81], off nt
	v_addc_co_u32_e32 v33, vcc, 0, v79, vcc
	global_load_dwordx4 v[74:77], v[30:31], off nt
	global_load_dwordx4 v[78:81], v[32:33], off nt
.Lt5_a:
	s_add_i32 s22, s19, 1
	s_cmp_lt_i32 s22, s100
	s_cbranch_scc0 .Lt5_a_w0
	s_waitcnt vmcnt(4)
	s_branch .Lt5_a_w1

; __device__ __forceinline__ unsigned cvt_pk_bf16(float lo, float hi) { unsigned r; asm volatile("v_cvt_pk_bf16_f32 %0, %1, %2" : "=v"(r) : "v"(lo), "v"(hi)); return r; }
; template <bool REMAP = false>
; __device__ __forceinline__ void transpose_convert(LAS unsigned char* lds, const float* src, bf16_t* dst, int K, int N, int G, int bid) {
;     ...
;         asm volatile("s_waitcnt lgkmcnt(0)" ::: "memory"); __builtin_amdgcn_s_barrier(); asm volatile("" ::: "memory");
; #pragma unroll
;         for (int i = 0; i < 4; ++i) {
; #pragma unroll
;             for (int j = 0; j < 4; ++j) tile[(r0 + 32 * i) * 65 + c4 * 4 + j] = v[i][j]; }
;         asm volatile("s_waitcnt lgkmcnt(0)" ::: "memory"); __builtin_amdgcn_s_barrier(); asm volatile("" ::: "memory");
;         if (t + G < ntiles) { const int k1 = ((t + G) / ntn) * 128, n1 = ((t + G) % ntn) * 64;
; #pragma unroll
;             for (int i = 0; i < 4; ++i) v[i] = __builtin_nontemporal_load((const f32x4*)(src + (size_t)(k1 + r0 + 32 * i) * N + n1 + c4 * 4)); }
; #pragma unroll
;         for (int i = 0; i < 2; ++i) { const int id = tid + 512 * i, n = id >> 4, kc = id & 15;
;             float f[8];
; #pragma unroll
;             for (int j = 0; j < 8; ++j) f[j] = tile[(kc * 8 + j) * 65 + n];
;             u32x4 w; w.x = cvt_pk_bf16(f[0], f[1]); w.y = cvt_pk_bf16(f[2], f[3]); w.z = cvt_pk_bf16(f[4], f[5]); w.w = cvt_pk_bf16(f[6], f[7]);
;             const int nd = !REMAP ? n0 : (n0 < 2048 ? (n0 >> 7) * 256 + (n0 & 127) : (n0 < 4096 ? n0 + 2048 : ((n0 - 4096) >> 7) * 256 + 128 + (n0 & 127)));
;             *(u32x4*)(dst + (size_t)(nd + n) * K + k0 + kc * 8) = w; }
.Lt5_a_w1:
	s_waitcnt lgkmcnt(0)
	s_barrier
	ds_write2_b32 v22, v0, v1 offset1:1
	ds_write2_b32 v22, v2, v3 offset0:2 offset1:3
	ds_write2_b32 v23, v4, v5 offset1:1
	ds_write2_b32 v24, v6, v7 offset1:1
	ds_write2_b32 v25, v8, v9 offset1:1
	ds_write2_b32 v28, v10, v11 offset1:1
	ds_write2_b32 v29, v12, v13 offset1:1
	ds_write2_b32 v47, v14, v15 offset1:1
	s_waitcnt lgkmcnt(0)
	s_barrier
	s_lshl_b32 s18, s19, 6
	s_ashr_i32 s6, s19, 31
	s_lshr_b32 s6, s6, 25
	s_add_i32 s19, s19, s6
	s_and_b32 s6, s19, 0xffffff80
	ds_read2_b32 v[30:31], v26 offset1:65
	ds_read2_b32 v[32:33], v26 offset0:130 offset1:195
	v_add_u32_e32 v36, 0x400, v26
	s_ashr_i32 s7, s6, 31
	ds_read2_b32 v[34:35], v36 offset0:4 offset1:69
	ds_read2_b32 v[36:37], v36 offset0:134 offset1:199
	v_lshl_add_u64 v[38:39], s[6:7], 1, v[18:19]
	s_lshl_b32 s6, s19, 6
	s_and_b32 s6, s6, 0xffffe000
	s_sub_i32 s6, s18, s6
	s_waitcnt lgkmcnt(3)
	v_cvt_pk_bf16_f32 v30, v30, v31
	s_waitcnt lgkmcnt(2)
	v_cvt_pk_bf16_f32 v31, v32, v33
	s_waitcnt lgkmcnt(1)
	v_cvt_pk_bf16_f32 v32, v34, v35
	v_add_u32_e32 v34, s6, v214
	v_ashrrev_i32_e32 v35, 31, v34
	v_lshlrev_b64 v[34:35], 12, v[34:35]
	v_add_u32_e32 v44, 0x400, v27
	s_waitcnt lgkmcnt(0)
	v_cvt_pk_bf16_f32 v33, v36, v37
	v_lshl_add_u64 v[34:35], v[38:39], 0, v[34:35]
	ds_read2_b32 v[36:37], v27 offset1:65
	ds_read2_b32 v[40:41], v27 offset0:130 offset1:195
	ds_read2_b32 v[42:43], v44 offset0:4 offset1:69
	ds_read2_b32 v[44:45], v44 offset0:134 offset1:199
	global_store_dwordx4 v[34:35], v[30:33], off
	v_add_u32_e32 v34, s6, v21
	v_ashrrev_i32_e32 v35, 31, v34
	v_lshlrev_b64 v[34:35], 12, v[34:35]
	v_lshl_add_u64 v[34:35], v[38:39], 0, v[34:35]
	s_waitcnt lgkmcnt(3)
	v_cvt_pk_bf16_f32 v30, v36, v37
	s_waitcnt lgkmcnt(2)
	v_cvt_pk_bf16_f32 v31, v40, v41
	s_waitcnt lgkmcnt(1)
	v_cvt_pk_bf16_f32 v32, v42, v43
	s_waitcnt lgkmcnt(0)
	v_cvt_pk_bf16_f32 v33, v44, v45
	global_store_dwordx4 v[34:35], v[30:33], off
	s_add_i32 s22, s19, 2
	s_cmp_lt_i32 s22, s100
	s_cbranch_scc0 .Lt5_a_nl
	s_and_b32 s7, s22, 0xffffff80
	s_lshl_b32 s23, s22, 6
	s_and_b32 s6, s23, 0xffffe000
	s_sub_i32 s6, s23, s6
	v_or_b32_e32 v8, s7, v214
	s_ashr_i32 s7, s6, 31
	v_ashrrev_i32_e32 v9, 31, v8
	v_lshl_add_u64 v[10:11], s[6:7], 2, v[16:17]
	v_lshlrev_b64 v[0:1], 15, v[8:9]
	v_lshl_add_u64 v[12:13], v[10:11], 0, v[0:1]
	v_or_b32_e32 v8, 64, v8
	v_add_co_u32_e32 v14, vcc, s3, v12
	v_ashrrev_i32_e32 v9, 31, v8
	s_nop 0
	v_addc_co_u32_e32 v15, vcc, 0, v13, vcc
	v_lshlrev_b64 v[8:9], 15, v[8:9]
	v_lshl_add_u64 v[30:31], v[10:11], 0, v[8:9]
	v_add_co_u32_e32 v32, vcc, s16, v12
	global_load_dwordx4 v[0:3], v[12:13], off nt
	global_load_dwordx4 v[4:7], v[14:15], off nt
	v_addc_co_u32_e32 v33, vcc, 0, v13, vcc
	global_load_dwordx4 v[8:11], v[30:31], off nt
	global_load_dwordx4 v[12:15], v[32:33], off nt
.Lt5_a_nl:
	s_add_i32 s19, s19, 1
	s_cmp_ge_i32 s19, s100
	s_cbranch_scc1 .LBB0_424

; __device__ __forceinline__ unsigned cvt_pk_bf16(float lo, float hi) { unsigned r; asm volatile("v_cvt_pk_bf16_f32 %0, %1, %2" : "=v"(r) : "v"(lo), "v"(hi)); return r; }
; template <bool REMAP = false>
; __device__ __forceinline__ void transpose_convert(LAS unsigned char* lds, const float* src, bf16_t* dst, int K, int N, int G, int bid) {
;     ...
;         asm volatile("s_waitcnt lgkmcnt(0)" ::: "memory"); __builtin_amdgcn_s_barrier(); asm volatile("" ::: "memory");
; #pragma unroll
;         for (int i = 0; i < 4; ++i) {
; #pragma unroll
;             for (int j = 0; j < 4; ++j) tile[(r0 + 32 * i) * 65 + c4 * 4 + j] = v[i][j]; }
;         asm volatile("s_waitcnt lgkmcnt(0)" ::: "memory"); __builtin_amdgcn_s_barrier(); asm volatile("" ::: "memory");
;         if (t + G < ntiles) { const int k1 = ((t + G) / ntn) * 128, n1 = ((t + G) % ntn) * 64;
; #pragma unroll
;             for (int i = 0; i < 4; ++i) v[i] = __builtin_nontemporal_load((const f32x4*)(src + (size_t)(k1 + r0 + 32 * i) * N + n1 + c4 * 4)); }
; #pragma unroll
;         for (int i = 0; i < 2; ++i) { const int id = tid + 512 * i, n = id >> 4, kc = id & 15;
;             float f[8];
; #pragma unroll
;             for (int j = 0; j < 8; ++j) f[j] = tile[(kc * 8 + j) * 65 + n];
;             u32x4 w; w.x = cvt_pk_bf16(f[0], f[1]); w.y = cvt_pk_bf16(f[2], f[3]); w.z = cvt_pk_bf16(f[4], f[5]); w.w = cvt_pk_bf16(f[6], f[7]);
;             const int nd = !REMAP ? n0 : (n0 < 2048 ? (n0 >> 7) * 256 + (n0 & 127) : (n0 < 4096 ? n0 + 2048 : ((n0 - 4096) >> 7) * 256 + 128 + (n0 & 127)));
;             *(u32x4*)(dst + (size_t)(nd + n) * K + k0 + kc * 8) = w; }
.Lt5_b_w1:
	s_waitcnt lgkmcnt(0)
	s_barrier
	ds_write2_b32 v22, v66, v67 offset1:1
	ds_write2_b32 v22, v68, v69 offset0:2 offset1:3
	ds_write2_b32 v23, v70, v71 offset1:1
	ds_write2_b32 v24, v72, v73 offset1:1
	ds_write2_b32 v25, v74, v75 offset1:1
	ds_write2_b32 v28, v76, v77 offset1:1
	ds_write2_b32 v29, v78, v79 offset1:1
	ds_write2_b32 v47, v80, v81 offset1:1
	s_waitcnt lgkmcnt(0)
	s_barrier
	s_lshl_b32 s18, s19, 6
	s_ashr_i32 s6, s19, 31
	s_lshr_b32 s6, s6, 25
	s_add_i32 s19, s19, s6
	s_and_b32 s6, s19, 0xffffff80
	ds_read2_b32 v[30:31], v26 offset1:65
	ds_read2_b32 v[32:33], v26 offset0:130 offset1:195
	v_add_u32_e32 v36, 0x400, v26
	s_ashr_i32 s7, s6, 31
	ds_read2_b32 v[34:35], v36 offset0:4 offset1:69
	ds_read2_b32 v[36:37], v36 offset0:134 offset1:199
	v_lshl_add_u64 v[38:39], s[6:7], 1, v[18:19]
	s_lshl_b32 s6, s19, 6
	s_and_b32 s6, s6, 0xffffe000
	s_sub_i32 s6, s18, s6
	s_waitcnt lgkmcnt(3)
	v_cvt_pk_bf16_f32 v30, v30, v31
	s_waitcnt lgkmcnt(2)
	v_cvt_pk_bf16_f32 v31, v32, v33
	s_waitcnt lgkmcnt(1)
	v_cvt_pk_bf16_f32 v32, v34, v35
	v_add_u32_e32 v34, s6, v214
	v_ashrrev_i32_e32 v35, 31, v34
	v_lshlrev_b64 v[34:35], 12, v[34:35]
	v_add_u32_e32 v44, 0x400, v27
	s_waitcnt lgkmcnt(0)
	v_cvt_pk_bf16_f32 v33, v36, v37
	v_lshl_add_u64 v[34:35], v[38:39], 0, v[34:35]
	ds_read2_b32 v[36:37], v27 offset1:65
	ds_read2_b32 v[40:41], v27 offset0:130 offset1:195
	ds_read2_b32 v[42:43], v44 offset0:4 offset1:69
	ds_read2_b32 v[44:45], v44 offset0:134 offset1:199
	global_store_dwordx4 v[34:35], v[30:33], off
	v_add_u32_e32 v34, s6, v21
	v_ashrrev_i32_e32 v35, 31, v34
	v_lshlrev_b64 v[34:35], 12, v[34:35]
	v_lshl_add_u64 v[34:35], v[38:39], 0, v[34:35]
	s_waitcnt lgkmcnt(3)
	v_cvt_pk_bf16_f32 v30, v36, v37
	s_waitcnt lgkmcnt(2)
	v_cvt_pk_bf16_f32 v31, v40, v41
	s_waitcnt lgkmcnt(1)
	v_cvt_pk_bf16_f32 v32, v42, v43
	s_waitcnt lgkmcnt(0)
	v_cvt_pk_bf16_f32 v33, v44, v45
	global_store_dwordx4 v[34:35], v[30:33], off
	s_add_i32 s22, s19, 2
	s_cmp_lt_i32 s22, s100
	s_cbranch_scc0 .Lt5_b_nl
	s_and_b32 s7, s22, 0xffffff80
	s_lshl_b32 s23, s22, 6
	s_and_b32 s6, s23, 0xffffe000
	s_sub_i32 s6, s23, s6
	v_or_b32_e32 v74, s7, v214
	s_ashr_i32 s7, s6, 31
	v_ashrrev_i32_e32 v75, 31, v74
	v_lshl_add_u64 v[76:77], s[6:7], 2, v[16:17]
	v_lshlrev_b64 v[66:67], 15, v[74:75]
	v_lshl_add_u64 v[78:79], v[76:77], 0, v[66:67]
	v_or_b32_e32 v74, 64, v74
	v_add_co_u32_e32 v80, vcc, s3, v78
	v_ashrrev_i32_e32 v75, 31, v74
	s_nop 0
	v_addc_co_u32_e32 v81, vcc, 0, v79, vcc
	v_lshlrev_b64 v[74:75], 15, v[74:75]
	v_lshl_add_u64 v[30:31], v[76:77], 0, v[74:75]
	v_add_co_u32_e32 v32, vcc, s16, v78
	global_load_dwordx4 v[66:69], v[78:79], off nt
	global_load_dwordx4 v[70:73], v[80:81], off nt
	v_addc_co_u32_e32 v33, vcc, 0, v79, vcc
	global_load_dwordx4 v[74:77], v[30:31], off nt
	global_load_dwordx4 v[78:81], v[32:33], off nt
.Lt5_b_nl:
	s_add_i32 s19, s19, 1
	s_cmp_ge_i32 s19, s100
	s_cbranch_scc1 .LBB0_424
	s_branch .Lt5_a
